# also seam 1 (P1->P2) XCD-local, with P1 rows mapped XCD-locally in P2's consumption order
# speedup vs baseline: 1.0138x; 1.0043x over previous
.LBB0_137:
	v_and_b32_e32 v0, 63, v210
	v_lshlrev_b32_e32 v0, 2, v0
	v_add_u32_e32 v0, 0x3700, v0
	v_readlane_b32 s0, v254, 10
	v_readlane_b32 s1, v254, 11
	s_nop 4
	global_load_dword v1, v0, s[0:1] sc1
	global_load_dword v2, v0, s[0:1] offset:256 sc1
	s_waitcnt vmcnt(0)
	v_cmp_ne_u32_e32 vcc, 0, v1
	s_nop 1
	s_bcnt1_i32_b64 s0, vcc
	v_cmp_ne_u32_e32 vcc, 0, v2
	s_nop 1
	s_bcnt1_i32_b64 s1, vcc
	s_add_i32 s0, s0, s1
	s_sub_i32 s0, s0, 8
	s_nop 3
	v_writelane_b32 v255, s0, 0
	s_cmp_lt_i32 s82, 2
	s_cselect_b64 s[0:1], -1, 0
	s_add_u32 s24, s78, 0x17e00000
	s_addc_u32 s25, s79, 0
	s_and_b64 s[4:5], s[0:1], s[4:5]
	s_cmp_lt_i32 s80, 0xa000
	s_cselect_b64 s[0:1], -1, 0
	v_writelane_b32 v254, s0, 50
	v_lshlrev_b32_e32 v216, 2, v217
	v_lshlrev_b32_e32 v212, 4, v217
	v_writelane_b32 v254, s1, 51
	s_and_b64 s[0:1], s[4:5], s[0:1]
	s_andn2_b64 vcc, exec, s[0:1]
	v_lshlrev_b32_e32 v214, 3, v217
	v_mbcnt_lo_u32_b32 v211, -1, 0
	s_cbranch_vccnz .LBB0_146
	s_lshr_b32 s52, s80, 8
	s_mulk_i32 s52, 0x1400
	s_and_b32 s53, s80, 0xff
	s_add_i32 s52, s52, s53
	s_add_i32 s54, s52, 0x1400
	s_mov_b32 s53, 0
	s_movk_i32 s8, 0x200
	s_add_i32 s14, s52, 0x100
	s_ashr_i32 s81, s80, 31
	s_ashr_i32 s9, s8, 31
	s_ashr_i32 s15, s14, 31
	v_mov_b32_e32 v33, 0
	v_readlane_b32 s36, v254, 12
	v_or_b32_e32 v4, 0x300, v216
	s_lshl_b64 s[10:11], s[52:53], 11
	s_lshl_b64 s[12:13], s[8:9], 11
	s_lshl_b64 s[0:1], s[14:15], 12
	v_mbcnt_hi_u32_b32 v47, -1, v211
	v_mov_b32_e32 v213, v33
	v_readlane_b32 s40, v254, 16
	v_readlane_b32 s41, v254, 17
	v_or_b32_e32 v0, 0x100, v216
	v_or_b32_e32 v2, 0x200, v216
	v_mov_b32_e32 v215, v33
	v_lshlrev_b32_e32 v32, 1, v4
	s_add_u32 s20, s16, s0
	v_and_b32_e32 v1, 64, v47
	s_mov_b32 s7, 0
	v_lshl_add_u64 v[34:35], s[40:41], 0, v[212:213]
	v_lshl_add_u64 v[36:37], s[24:25], 0, v[214:215]
	v_lshl_add_u64 v[38:39], s[24:25], 0, v[32:33]
	v_lshl_add_u64 v[40:41], s[78:79], 0, v[214:215]
	s_addc_u32 s21, s17, s1
	s_lshl_b64 s[22:23], s[8:9], 12
	v_mov_b32_e32 v44, 0x358637bd
	s_mov_b32 s3, 0xf800000
	v_mov_b32_e32 v45, 0x260
	s_mov_b32 s35, 0x17e00000
	v_lshlrev_b32_e32 v32, 2, v4
	v_lshlrev_b32_e32 v46, 2, v216
	v_add_u32_e32 v48, 64, v1
	v_xor_b32_e32 v49, 1, v47
	v_xor_b32_e32 v50, 2, v47
	v_xor_b32_e32 v51, 4, v47
	v_xor_b32_e32 v52, 8, v47
	v_xor_b32_e32 v53, 16, v47
	v_xor_b32_e32 v54, 32, v47
	v_lshlrev_b32_e32 v55, 2, v0
	v_lshlrev_b32_e32 v56, 2, v2
	s_mov_b64 s[26:27], s[52:53]
	v_readlane_b32 s37, v254, 13
	v_readlane_b32 s38, v254, 14
	v_readlane_b32 s39, v254, 15
	v_readlane_b32 s42, v254, 18
	v_readlane_b32 s43, v254, 19
	v_readlane_b32 s44, v254, 20
	v_readlane_b32 s45, v254, 21
	v_readlane_b32 s46, v254, 22
	v_readlane_b32 s47, v254, 23
	v_readlane_b32 s48, v254, 24
	v_readlane_b32 s49, v254, 25
	v_readlane_b32 s50, v254, 26
	v_readlane_b32 s51, v254, 27
	s_branch .LBB0_141

.LBB0_141:
	s_add_i32 s0, s26, 0xffffe000
	s_add_u32 s46, s26, 0x100
	s_lshr_b32 s1, s0, 12
	s_cmpk_lt_i32 s26, 0x2000
	s_cselect_b32 s6, 8, s1
	s_cselect_b32 s1, s27, 0
	s_cselect_b32 s0, s26, s0
	s_cselect_b32 s28, s17, s19
	s_cselect_b32 s29, s16, s18
	s_lshl_b64 s[0:1], s[0:1], 12
	s_add_u32 s42, s29, s0
	s_addc_u32 s43, s28, s1
	s_mov_b64 s[0:1], -1
	s_cmp_gt_i32 s46, 0x9fff
	s_mulk_i32 s6, 0x1800
	v_lshl_add_u64 v[42:43], v[40:41], 0, s[10:11]
	s_cbranch_scc0 .LBB0_143
	global_load_dwordx4 v[4:7], v46, s[42:43]
	global_load_dwordx4 v[8:11], v46, s[42:43] offset:1024
	global_load_dwordx4 v[0:3], v46, s[42:43] offset:3072
	global_load_dwordx4 v[12:15], v46, s[42:43] offset:2048
	s_lshl_b64 s[0:1], s[6:7], 2
	s_add_u32 s28, s78, s0
	s_addc_u32 s29, s79, s1
	s_add_u32 s30, s28, 0x1000
	s_addc_u32 s31, s29, 0
	v_cmp_lt_i32_e32 vcc, v49, v48
	global_load_dwordx4 v[16:19], v46, s[30:31]
	global_load_dwordx4 v[20:23], v[34:35], off
	v_cndmask_b32_e32 v24, v47, v49, vcc
	v_lshlrev_b32_e32 v57, 2, v24
	global_load_dwordx4 v[24:27], v46, s[28:29]
	v_cmp_lt_i32_e32 vcc, v50, v48
	s_waitcnt vmcnt(6)
	v_pk_mul_f32 v[28:29], v[6:7], v[6:7]
	v_pk_mul_f32 v[30:31], v[4:5], v[4:5]
	s_waitcnt vmcnt(5)
	v_pk_mul_f32 v[58:59], v[10:11], v[10:11]
	v_pk_mul_f32 v[60:61], v[8:9], v[8:9]
	v_pk_mov_b32 v[66:67], v[30:31], v[28:29] op_sel:[1,0]
	v_mov_b32_e32 v31, v29
	v_pk_mov_b32 v[28:29], v[60:61], v[58:59] op_sel:[1,0]
	v_mov_b32_e32 v61, v59
	s_waitcnt vmcnt(4)
	v_mul_f32_e32 v65, v0, v0
	s_waitcnt vmcnt(3)
	v_mul_f32_e32 v62, v13, v13
	v_mul_f32_e32 v64, v15, v15
	v_pk_add_f32 v[30:31], v[66:67], v[30:31]
	v_pk_add_f32 v[28:29], v[28:29], v[60:61]
	v_mul_f32_e32 v68, v1, v1
	v_mul_f32_e32 v69, v2, v2
	v_mul_f32_e32 v70, v3, v3
	v_pk_fma_f32 v[58:59], v[12:13], v[12:13], v[62:63] op_sel_hi:[1,1,0]
	v_pk_fma_f32 v[62:63], v[14:15], v[14:15], v[64:65] op_sel_hi:[1,1,0]
	v_pk_add_f32 v[30:31], v[30:31], v[30:31] op_sel:[0,1] op_sel_hi:[1,0]
	v_pk_add_f32 v[28:29], v[28:29], v[28:29] op_sel:[0,1] op_sel_hi:[1,0]
	v_mov_b32_e32 v59, v69
	v_mov_b32_e32 v63, v70
	v_mov_b32_e32 v31, v65
	v_mov_b32_e32 v29, v68
	v_pk_add_f32 v[58:59], v[58:59], v[62:63]
	v_pk_add_f32 v[28:29], v[30:31], v[28:29]
	v_cndmask_b32_e32 v30, v47, v50, vcc
	v_pk_add_f32 v[28:29], v[28:29], v[58:59]
	v_lshlrev_b32_e32 v30, 2, v30
	v_add_f32_e32 v28, v28, v29
	ds_bpermute_b32 v29, v57, v28
	v_cmp_lt_i32_e32 vcc, v51, v48
	s_waitcnt vmcnt(2)
	v_pk_add_f32 v[18:19], v[18:19], 1.0 op_sel_hi:[1,0]
	v_pk_add_f32 v[16:17], v[16:17], 1.0 op_sel_hi:[1,0]
	s_waitcnt lgkmcnt(0)
	v_add_f32_e32 v28, v28, v29
	ds_bpermute_b32 v29, v30, v28
	v_cndmask_b32_e32 v30, v47, v51, vcc
	v_lshlrev_b32_e32 v30, 2, v30
	v_cmp_lt_i32_e32 vcc, v52, v48
	s_waitcnt lgkmcnt(0)
	v_add_f32_e32 v28, v28, v29
	ds_bpermute_b32 v29, v30, v28
	v_cndmask_b32_e32 v30, v47, v52, vcc
	v_lshlrev_b32_e32 v30, 2, v30
	v_cmp_lt_i32_e32 vcc, v53, v48
	s_waitcnt lgkmcnt(0)
	v_add_f32_e32 v28, v28, v29
	ds_bpermute_b32 v29, v30, v28
	v_cndmask_b32_e32 v30, v47, v53, vcc
	v_lshlrev_b32_e32 v30, 2, v30
	v_cmp_lt_i32_e32 vcc, v54, v48
	s_waitcnt lgkmcnt(0)
	v_add_f32_e32 v28, v28, v29
	ds_bpermute_b32 v29, v30, v28
	v_cndmask_b32_e32 v30, v47, v54, vcc
	v_lshlrev_b32_e32 v30, 2, v30
	s_waitcnt lgkmcnt(0)
	v_add_f32_e32 v28, v28, v29
	ds_bpermute_b32 v29, v30, v28
	s_waitcnt lgkmcnt(0)
	v_add_f32_e32 v28, v28, v29
	v_fmamk_f32 v28, v28, 0x3a800000, v44
	v_mul_f32_e32 v29, 0x4f800000, v28
	v_cmp_gt_f32_e32 vcc, s3, v28
	s_nop 1
	v_cndmask_b32_e32 v30, v28, v29, vcc
	v_sqrt_f32_e32 v31, v30
	v_add_co_u32_e64 v28, s[0:1], s35, v42
	v_add_u32_e32 v57, -1, v31
	s_nop 0
	v_addc_co_u32_e64 v29, s[0:1], 0, v43, s[0:1]
	v_add_u32_e32 v58, 1, v31
	v_fma_f32 v59, -v57, v31, v30
	v_fma_f32 v60, -v58, v31, v30
	v_cmp_ge_f32_e64 s[0:1], 0, v59
	s_nop 1
	v_cndmask_b32_e64 v31, v31, v57, s[0:1]
	v_cmp_lt_f32_e64 s[0:1], 0, v60
	s_nop 1
	v_cndmask_b32_e64 v31, v31, v58, s[0:1]
	v_mul_f32_e32 v57, 0x37800000, v31
	v_cndmask_b32_e32 v31, v31, v57, vcc
	v_cmp_class_f32_e32 vcc, v30, v45
	s_nop 1
	v_cndmask_b32_e32 v30, v31, v30, vcc
	v_div_scale_f32 v31, s[0:1], v30, v30, 1.0
	v_rcp_f32_e32 v57, v31
	v_div_scale_f32 v58, vcc, 1.0, v30, 1.0
	s_mov_b64 s[0:1], 0
	v_fma_f32 v59, -v31, v57, 1.0
	v_fmac_f32_e32 v57, v59, v57
	v_mul_f32_e32 v59, v58, v57
	v_fma_f32 v60, -v31, v59, v58
	v_fmac_f32_e32 v59, v60, v57
	v_fma_f32 v31, -v31, v59, v58
	v_div_fmas_f32 v31, v31, v57, v59
	v_div_fixup_f32 v30, v31, v30, 1.0
	v_pk_mul_f32 v[6:7], v[6:7], v[30:31] op_sel_hi:[1,0]
	v_pk_mul_f32 v[4:5], v[4:5], v[30:31] op_sel_hi:[1,0]
	s_waitcnt vmcnt(1)
	v_pk_mul_f32 v[6:7], v[22:23], v[6:7]
	v_pk_mul_f32 v[4:5], v[20:21], v[4:5]
	s_waitcnt vmcnt(0)
	v_pk_fma_f32 v[6:7], v[18:19], v[6:7], v[26:27]
	v_pk_fma_f32 v[4:5], v[16:17], v[4:5], v[24:25]
	v_pk_mul_f32 v[10:11], v[10:11], v[30:31] op_sel_hi:[1,0]
	v_cvt_pk_bf16_f32 v4, v4, v5
	v_cvt_pk_bf16_f32 v5, v6, v7
	global_store_dwordx2 v[28:29], v[4:5], off
	global_load_dwordx4 v[4:7], v[34:35], off offset:1024
	s_nop 0
	global_load_dwordx4 v[16:19], v55, s[30:31]
	global_load_dwordx4 v[20:23], v46, s[28:29] offset:1024
	v_pk_mul_f32 v[8:9], v[8:9], v[30:31] op_sel_hi:[1,0]
	v_pk_mul_f32 v[14:15], v[14:15], v[30:31] op_sel_hi:[1,0]
	v_pk_mul_f32 v[12:13], v[12:13], v[30:31] op_sel_hi:[1,0]
	v_pk_mul_f32 v[2:3], v[2:3], v[30:31] op_sel_hi:[1,0]
	v_pk_mul_f32 v[0:1], v[0:1], v[30:31] op_sel_hi:[1,0]
	s_waitcnt vmcnt(2)
	v_pk_mul_f32 v[4:5], v[4:5], v[8:9]
	v_pk_mul_f32 v[6:7], v[6:7], v[10:11]
	s_waitcnt vmcnt(1)
	v_pk_add_f32 v[8:9], v[18:19], 1.0 op_sel_hi:[1,0]
	v_pk_add_f32 v[10:11], v[16:17], 1.0 op_sel_hi:[1,0]
	s_waitcnt vmcnt(0)
	v_pk_fma_f32 v[6:7], v[8:9], v[6:7], v[22:23]
	v_pk_fma_f32 v[4:5], v[10:11], v[4:5], v[20:21]
	s_nop 0
	v_cvt_pk_bf16_f32 v4, v4, v5
	v_cvt_pk_bf16_f32 v5, v6, v7
	global_store_dwordx2 v[28:29], v[4:5], off offset:512
	global_load_dwordx4 v[4:7], v[34:35], off offset:2048
	s_nop 0
	global_load_dwordx4 v[8:11], v56, s[30:31]
	global_load_dwordx4 v[16:19], v46, s[28:29] offset:2048
	s_waitcnt vmcnt(2)
	v_pk_mul_f32 v[4:5], v[4:5], v[12:13]
	v_pk_mul_f32 v[6:7], v[6:7], v[14:15]
	s_waitcnt vmcnt(1)
	v_pk_add_f32 v[10:11], v[10:11], 1.0 op_sel_hi:[1,0]
	v_pk_add_f32 v[8:9], v[8:9], 1.0 op_sel_hi:[1,0]
	s_waitcnt vmcnt(0)
	v_pk_fma_f32 v[6:7], v[6:7], v[10:11], v[18:19]
	v_pk_fma_f32 v[4:5], v[4:5], v[8:9], v[16:17]
	s_nop 0
	v_cvt_pk_bf16_f32 v4, v4, v5
	v_cvt_pk_bf16_f32 v5, v6, v7
	global_store_dwordx2 v[28:29], v[4:5], off offset:1024
	global_load_dwordx4 v[4:7], v[34:35], off offset:3072
	s_waitcnt vmcnt(0)
	v_pk_mul_f32 v[0:1], v[0:1], v[4:5]
	v_pk_mul_f32 v[2:3], v[2:3], v[6:7]
